# code placement: 16 bytes of padding at the layer-loop head (hot loops shifted by 16 B); otherwise identical to the previous version
# speedup vs baseline: 1.0611x; 1.0012x over previous
.LBB0_185:
	s_nop 0
	s_nop 0
	s_nop 0
	s_nop 0
	s_and_b64 s[0:1], s[78:79], exec
	v_readlane_b32 s0, v235, 27
	v_readlane_b32 s1, v235, 28
	v_readlane_b32 s6, v236, 12
	s_cselect_b32 s57, s0, s1
	v_readlane_b32 s0, v235, 29
	v_readlane_b32 s1, v235, 30
	v_mov_b32_e32 v8, v194
	v_readlane_b32 s7, v236, 13
	s_cselect_b32 s58, s0, s1
	v_cmp_ne_u32_e64 s[0:1], 1, v196
	s_andn2_b64 vcc, exec, s[6:7]
	v_readfirstlane_b32 s16, v8
	s_cbranch_vccnz .LBB0_187
	s_and_b64 s[8:9], s[78:79], exec
	v_readlane_b32 s6, v234, 19
	s_cselect_b32 s8, 20, 19
	v_readlane_b32 s7, v234, 20
	s_lshl_b64 s[8:9], s[6:7], s8
	s_add_u32 s40, s84, s8
	s_addc_u32 s41, s85, s9
	v_readlane_b32 s8, v234, 22
	v_readlane_b32 s9, v234, 23
	s_add_u32 s42, s58, s8
	s_addc_u32 s43, s57, s9
	v_readlane_b32 s70, v234, 21
	s_bitcmp1_b32 s2, 0
	s_cbranch_scc0 .Lmy_g1ord
	s_add_u32 s42, s42, 0x800000
	s_addc_u32 s43, s43, 0
	s_add_i32 s70, s70, 16
